# per-layer prep fully hidden: FFN/GLU weight conversion on gemm_in's 112 short workgroups, S5 discretisation after workgroup 255's ffn_down filter item; norm1 phase of layers 1..3 is the norm only
# speedup vs baseline: 1.0316x; 1.0163x over previous
.LBB0_14:
	v_readlane_b32 s0, v249, 49
	v_readlane_b32 s4, v249, 47
	v_readlane_b32 s1, v251, 0
	s_cmp_lg_u32 s84, 0x100
	s_cbranch_scc1 .Lpp_nof
	s_cmp_lg_u32 s0, 1
	s_cbranch_scc1 .Lpp_no1
	s_cmp_lt_i32 s4, 1
	s_cbranch_scc1 .Lpp_nof
	s_cmp_lt_u32 s1, 0x90
	s_cbranch_scc1 .Lpp_nof
	s_movk_i32 s101, 0x3000
	s_add_i32 s23, s1, 0x2d0
	s_movk_i32 s26, 0x70
	v_readlane_b32 s5, v249, 48
	s_mov_b64 s[20:21], -1
	s_mov_b64 s[24:25], -1
	s_mov_b64 s[0:1], -1
	s_branch .Lpp_conv_fb
.Lpp_no1:
	s_cmp_gt_i32 s4, 2
	s_cbranch_scc1 .Lpp_nof
	s_cmp_eq_u32 s0, 9
	s_cbranch_scc1 .Lpp_f9
	s_cmp_lt_u32 s1, 0xc0
	s_cbranch_scc1 .Lpp_nof
	s_cmp_eq_u32 s0, 7
	s_cbranch_scc1 .Lpp_f7
	s_cmp_eq_u32 s0, 10
	s_cbranch_scc0 .Lpp_nof
	s_add_i32 s6, s1, 0xffffff80
	s_branch .Lpp_f

.Lpp_nof:
	s_cmp_eq_u32 s0, 0
	s_cselect_b64 s[0:1], -1, 0
	s_cmp_gt_i32 s4, 0
	s_cselect_b64 s[20:21], -1, 0
	s_and_b64 s[20:21], s[0:1], s[20:21]
	v_readlane_b32 s5, v249, 48
	s_andn2_b64 vcc, exec, s[20:21]
	s_cbranch_vccnz .LBB0_352
	s_cmp_lg_u32 s84, 0x100
	s_cbranch_scc1 .LBB0_55
	s_branch .LBB0_352

.LBB0_64:
	s_cmpk_eq_u32 s101, 0x4000
	s_cbranch_scc1 .LBB0_352
	s_mov_b32 s0, s84
	s_cmpk_lt_i32 s0, 0xc8
	s_mov_b64 s[0:1], -1
	s_cbranch_scc0 .LBB0_206
	v_readlane_b32 s23, v251, 0
	s_cmpk_gt_i32 s23, 0x87
	s_cbranch_scc1 .LBB0_108
	v_readlane_b32 s0, v249, 47
	s_mov_b32 s6, s0
	s_mov_b32 s4, s6
	v_readlane_b32 s1, v249, 48
	s_ashr_i32 s7, s0, 31
	s_lshl_b32 s0, s0, 6
	v_writelane_b32 v249, s4, 47
	s_lshl_b32 s34, s6, 10
	s_ashr_i32 s1, s0, 31
	s_lshl_b64 s[20:21], s[6:7], 14
	s_mul_hi_i32 s26, s6, 0x2100
	s_mul_i32 s29, s6, 0x2100
	s_lshl_b64 s[30:31], s[6:7], 18
	v_writelane_b32 v249, s5, 48
	s_ashr_i32 s35, s34, 31
	v_readlane_b32 s4, v250, 59
	v_readlane_b32 s5, v250, 60
	s_add_u32 s20, s4, s20
	v_readlane_b32 s6, v250, 61
	s_addc_u32 s21, s5, s21
	s_lshl_b64 s[0:1], s[0:1], 2
	v_readlane_b32 s7, v250, 62
	s_add_u32 s24, s6, s0
	v_readlane_b32 s10, v249, 1
	s_addc_u32 s25, s7, s1
	v_readlane_b32 s11, v249, 2
	s_add_u32 s42, s10, s0
	v_readlane_b32 s44, v250, 12
	s_addc_u32 s43, s11, s1
	v_readlane_b32 s58, v250, 26
	v_readlane_b32 s45, v250, 13
	v_readlane_b32 s59, v250, 27
	s_add_u32 s44, s58, s0
	v_readlane_b32 s46, v250, 14
	v_readlane_b32 s56, v250, 24
	s_addc_u32 s45, s59, s1
	v_readlane_b32 s47, v250, 15
	v_readlane_b32 s57, v250, 25
	s_add_u32 s46, s56, s29
	v_readlane_b32 s8, v250, 63
	s_addc_u32 s47, s57, s26
	v_readlane_b32 s9, v249, 0
	s_add_u32 s29, s8, s30
	v_readlane_b32 s12, v249, 3
	v_readlane_b32 s48, v250, 16
	s_addc_u32 s30, s9, s31
	s_lshl_b64 s[0:1], s[34:35], 2
	v_readlane_b32 s13, v249, 4
	v_readlane_b32 s49, v250, 17
	s_add_u32 s48, s12, s0
	s_addc_u32 s49, s13, s1
	v_readlane_b32 s14, v249, 5
	v_readlane_b32 s15, v249, 6
	v_readlane_b32 s16, v249, 7
	v_readlane_b32 s17, v249, 8
	v_readlane_b32 s18, v249, 9
	v_readlane_b32 s19, v249, 10
	v_readlane_b32 s50, v250, 18
	v_readlane_b32 s51, v250, 19
	v_readlane_b32 s52, v250, 20
	v_readlane_b32 s53, v250, 21
	v_readlane_b32 s54, v250, 22
	v_readlane_b32 s55, v250, 23

.LBB0_352:
	s_cmp_eq_u32 s101, 0
	s_cbranch_scc1 .Lpp_norm
	s_cmpk_eq_u32 s101, 0x1000
	s_cbranch_scc1 .Lpp_clr
	s_cmpk_eq_u32 s101, 0x3000
	s_cbranch_scc1 .Lpp_clr
	s_cmpk_eq_u32 s101, 0x2000
	s_cbranch_scc0 .Lpp_done
	v_readlane_b32 s4, v249, 47
	s_movk_i32 s100, 0x790
	s_add_i32 s4, s4, -1
	s_nop 1
	v_writelane_b32 v249, s4, 47
	s_branch .Lpp_clr
.Lpp_done:
	s_cmpk_eq_u32 s101, 0x4000
	s_cbranch_scc1 .Lpp_s5ret
	v_readlane_b32 s0, v249, 49
	s_cmpk_lg_u32 s101, 0x100
	s_cbranch_scc1 .Lpp_rest
	s_cmp_lg_u32 s0, 10
	s_cbranch_scc1 .Lpp_rest
	s_movk_i32 s1, 0xff
	s_movk_i32 s101, 0x4000
	s_nop 1
	v_writelane_b32 v251, s1, 0
	v_readlane_b32 s4, v249, 47
	v_readlane_b32 s5, v249, 48
	s_mov_b64 s[20:21], -1
	s_mov_b64 s[24:25], -1
	s_mov_b64 s[0:1], -1
	s_branch .LBB0_55
.Lpp_s5ret:
	v_readlane_b32 s4, v249, 47
	s_add_i32 s4, s4, -1
	s_nop 1
	v_writelane_b32 v249, s4, 47
	s_branch .Lpp_clr
